# v1 + attention unit prologue loads hoisted (tiles 0-2 together) + P9 next-row prefetch
# speedup vs baseline: 1.0040x; 1.0040x over previous
.LBB0_380:
	v_add_u32_e32 v3, s62, v187
	v_mov_b64_e32 v[4:5], s[96:97]
	v_mad_i64_i32 v[4:5], s[0:1], v3, s33, v[4:5]
	s_lshl_b32 s74, s3, 7
	v_lshl_add_u64 v[4:5], v[4:5], 0, s[74:75]
	v_mov_b32_e32 v197, v189
	v_lshl_add_u64 v[8:9], v[4:5], 0, v[196:197]
	global_load_dwordx4 v[4:7], v[8:9], off offset:2048
	s_nop 0
	global_load_dwordx4 v[8:11], v[8:9], off offset:2304
	s_cmp_lt_i32 s64, 1
	s_mov_b64 s[0:1], -1
	s_cbranch_scc0 .LBB0_382
	s_lshl_b32 s0, s68, 8
	s_lshl_b32 s1, s64, 6
	s_sub_i32 s0, s0, s1
	s_add_i32 s62, s0, 0x4000
	s_mov_b64 s[0:1], 0

.LBB0_384:
	s_lshl_b32 s3, s3, 6
	v_add_u32_e32 v76, s62, v187
	v_mov_b64_e32 v[74:75], s[96:97]
	v_mad_i64_i32 v[74:75], s[0:1], v76, s33, v[74:75]
	s_lshl_b32 s74, s3, 1
	v_lshl_add_u64 v[74:75], v[74:75], 0, s[74:75]
	v_mov_b32_e32 v197, v189
	v_lshl_add_u64 v[74:75], v[74:75], 0, v[196:197]
	global_load_dwordx4 v[78:81], v[74:75], off offset:2048
	global_load_dwordx4 v[82:85], v[74:75], off offset:2304
	s_cmp_lt_i32 s64, -2
	s_cbranch_scc1 .Lp3_t2_done
	s_cmp_lt_i32 s64, 2
	s_mov_b64 s[62:63], -1
	s_cbranch_scc0 .LBB0_387
	s_lshl_b32 s3, s68, 8
	s_lshl_b32 s62, s64, 6
	s_sub_i32 s3, s3, s62
	s_addk_i32 s3, 0x4040
	s_mov_b64 s[62:63], 0

.LBB0_389:
	v_add_u32_e32 v76, s3, v187
	v_mov_b64_e32 v[74:75], s[96:97]
	v_mad_i64_i32 v[74:75], s[62:63], v76, s33, v[74:75]
	v_lshl_add_u64 v[74:75], v[74:75], 0, s[74:75]
	v_mov_b32_e32 v197, v189
	v_lshl_add_u64 v[74:75], v[74:75], 0, v[196:197]
	global_load_dwordx4 v[66:69], v[74:75], off offset:2048
	global_load_dwordx4 v[70:73], v[74:75], off offset:2304
.Lp3_t2_done:
	s_barrier
	s_waitcnt vmcnt(3)
	ds_write_b128 v193, v[4:7]
	s_waitcnt vmcnt(2)
	ds_write_b128 v193, v[8:11] offset:9216
	s_waitcnt vmcnt(1)
	ds_write_b128 v193, v[78:81] offset:18432
	s_waitcnt vmcnt(0)
	ds_write_b128 v193, v[82:85] offset:27648
	s_cmp_gt_i32 s64, -3
	s_cselect_b64 s[0:1], -1, 0

.LBB0_1052:
	s_cmp_lt_i32 s90, 10
	s_cselect_b64 s[2:3], -1, 0
	s_and_b64 s[4:5], s[2:3], s[0:1]
	s_andn2_b64 vcc, exec, s[4:5]
	s_cbranch_vccnz .LBB0_1057
	v_lshrrev_b32_e32 v2, 6, v0
	s_waitcnt vmcnt(0)
	v_lshl_or_b32 v18, s58, 3, v2
	s_movk_i32 s0, 0x4000
	v_cmp_gt_i32_e32 vcc, s0, v18
	s_and_saveexec_b64 s[6:7], vcc
	s_cbranch_execz .LBB0_1056
	v_readlane_b32 s8, v251, 20
	v_and_b32_e32 v19, 0xfc0, v193
	v_readlane_b32 s16, v251, 28
	v_readlane_b32 s17, v251, 29
	s_nop 4
	global_load_dwordx4 v[2:5], v19, s[16:17]
	global_load_dwordx4 v[6:9], v19, s[16:17] offset:16
	global_load_dwordx4 v[10:13], v19, s[16:17] offset:32
	global_load_dwordx4 v[14:17], v19, s[16:17] offset:48
	v_mbcnt_lo_u32_b32 v19, -1, 0
	v_mbcnt_hi_u32_b32 v19, -1, v19
	v_and_b32_e32 v21, 64, v19
	v_xor_b32_e32 v20, 1, v19
	v_add_u32_e32 v21, 64, v21
	v_cmp_lt_i32_e32 vcc, v20, v21
	v_readlane_b32 s9, v251, 21
	v_readlane_b32 s12, v251, 24
	v_cndmask_b32_e32 v20, v19, v20, vcc
	v_lshlrev_b32_e32 v32, 2, v20
	v_xor_b32_e32 v20, 2, v19
	v_cmp_lt_i32_e32 vcc, v20, v21
	v_readlane_b32 s13, v251, 25
	v_readlane_b32 s14, v251, 26
	v_cndmask_b32_e32 v20, v19, v20, vcc
	v_lshlrev_b32_e32 v33, 2, v20
	v_xor_b32_e32 v20, 4, v19
	v_cmp_lt_i32_e32 vcc, v20, v21
	v_readlane_b32 s15, v251, 27
	v_readlane_b32 s20, v251, 32
	v_cndmask_b32_e32 v20, v19, v20, vcc
	v_lshlrev_b32_e32 v34, 2, v20
	v_xor_b32_e32 v20, 8, v19
	v_cmp_lt_i32_e32 vcc, v20, v21
	v_readlane_b32 s21, v251, 33
	s_mov_b64 s[8:9], s[16:17]
	v_cndmask_b32_e32 v19, v19, v20, vcc
	v_lshlrev_b32_e32 v35, 2, v19
	v_and_b32_e32 v19, 63, v0
	v_readlane_b32 s22, v251, 34
	v_readlane_b32 s23, v251, 35
	s_mov_b64 s[12:13], s[20:21]
	s_lshl_b32 s8, s69, 3
	v_lshlrev_b32_e32 v20, 5, v19
	v_ashrrev_i32_e32 v19, 31, v18
	v_readlane_b32 s10, v251, 22
	v_readlane_b32 s11, v251, 23
	v_readlane_b32 s18, v251, 30
	v_readlane_b32 s19, v251, 31
	s_mov_b64 s[14:15], s[22:23]
	s_movk_i32 s0, 0x1800
	v_mov_b64_e32 v[22:23], s[88:89]
	s_ashr_i32 s9, s8, 31
	v_lshlrev_b64 v[26:27], 11, v[18:19]
	v_mov_b32_e32 v21, 0
	v_mad_i64_i32 v[22:23], s[0:1], v18, s0, v[22:23]
	s_mul_i32 s10, s69, 0xc000
	s_mul_hi_i32 s11, s8, 0x1800
	v_lshl_add_u64 v[24:25], s[14:15], 0, v[26:27]
	s_lshl_b64 s[12:13], s[8:9], 11
	v_lshl_add_u64 v[26:27], s[88:89], 0, v[26:27]
	s_mov_b64 s[14:15], 0
	s_mov_b64 s[16:17], 0x2000000
	s_brev_b32 s2, 64
	s_mov_b64 s[18:19], 0x367e000
	s_mov_b32 s3, 0x367e000
	v_mov_b32_e32 v19, 0x358637bd
	s_mov_b32 s9, 0x800000
	s_mov_b32 s20, 0xa27d000
	s_movk_i32 s21, 0x3fff
	v_lshl_add_u64 v[124:125], v[24:25], 0, v[20:21]
	global_load_dwordx4 v[100:103], v[124:125], off offset:16
	global_load_dwordx4 v[104:107], v[124:125], off
	v_lshl_add_u64 v[126:127], v[124:125], 0, s[16:17]
	global_load_dwordx4 v[108:111], v[126:127], off offset:16
	global_load_dwordx4 v[112:115], v[126:127], off
	v_lshl_add_u64 v[126:127], v[22:23], 0, v[20:21]
	v_lshl_add_u64 v[126:127], v[126:127], 0, s[18:19]
	global_load_dwordx4 v[116:119], v[126:127], off offset:16
	global_load_dwordx4 v[120:123], v[126:127], off
	s_waitcnt vmcnt(0)
.LBB0_1055:
	v_lshl_add_u64 v[56:57], v[26:27], 0, v[20:21]
	v_add_co_u32_e32 v56, vcc, s20, v56
	v_add_u32_e32 v18, s8, v18
	s_nop 0
	v_addc_co_u32_e32 v57, vcc, 0, v57, vcc
	v_cmp_lt_i32_e64 s[0:1], s21, v18
	v_lshl_add_u64 v[22:23], v[22:23], 0, s[10:11]
	v_lshl_add_u64 v[24:25], v[24:25], 0, s[12:13]
	v_lshl_add_u64 v[26:27], v[26:27], 0, s[12:13]
	s_or_b64 s[14:15], s[0:1], s[14:15]
	s_waitcnt vmcnt(7)
	v_lshlrev_b32_e32 v58, 16, v103
	v_and_b32_e32 v59, 0xffff0000, v103
	v_lshlrev_b32_e32 v60, 16, v102
	v_and_b32_e32 v61, 0xffff0000, v102
	v_lshlrev_b32_e32 v38, 16, v101
	v_and_b32_e32 v39, 0xffff0000, v101
	v_lshlrev_b32_e32 v62, 16, v100
	v_and_b32_e32 v63, 0xffff0000, v100
	s_waitcnt vmcnt(6)
	v_lshlrev_b32_e32 v36, 16, v107
	v_and_b32_e32 v37, 0xffff0000, v107
	v_lshlrev_b32_e32 v64, 16, v106
	v_and_b32_e32 v65, 0xffff0000, v106
	v_lshlrev_b32_e32 v42, 16, v105
	v_and_b32_e32 v43, 0xffff0000, v105
	v_lshlrev_b32_e32 v66, 16, v104
	v_and_b32_e32 v67, 0xffff0000, v104
	s_waitcnt vmcnt(5)
	v_lshlrev_b32_e32 v40, 16, v111
	v_and_b32_e32 v41, 0xffff0000, v111
	v_lshlrev_b32_e32 v68, 16, v110
	v_and_b32_e32 v69, 0xffff0000, v110
	v_lshlrev_b32_e32 v46, 16, v109
	v_and_b32_e32 v47, 0xffff0000, v109
	v_lshlrev_b32_e32 v70, 16, v108
	v_and_b32_e32 v71, 0xffff0000, v108
	s_waitcnt vmcnt(4)
	v_lshlrev_b32_e32 v44, 16, v115
	v_and_b32_e32 v45, 0xffff0000, v115
	v_lshlrev_b32_e32 v72, 16, v114
	v_and_b32_e32 v73, 0xffff0000, v114
	v_lshlrev_b32_e32 v50, 16, v113
	v_and_b32_e32 v51, 0xffff0000, v113
	v_lshlrev_b32_e32 v74, 16, v112
	v_and_b32_e32 v75, 0xffff0000, v112
	v_pk_add_f32 v[40:41], v[58:59], v[40:41]
	s_waitcnt vmcnt(3)
	v_lshlrev_b32_e32 v48, 16, v119
	v_and_b32_e32 v49, 0xffff0000, v119
	v_pk_add_f32 v[58:59], v[60:61], v[68:69]
	v_lshlrev_b32_e32 v60, 16, v118
	v_and_b32_e32 v61, 0xffff0000, v118
	v_pk_add_f32 v[30:31], v[38:39], v[46:47]
	v_lshlrev_b32_e32 v38, 16, v117
	v_and_b32_e32 v39, 0xffff0000, v117
	v_pk_add_f32 v[46:47], v[62:63], v[70:71]
	v_lshlrev_b32_e32 v62, 16, v116
	v_and_b32_e32 v63, 0xffff0000, v116
	v_pk_add_f32 v[28:29], v[36:37], v[44:45]
	s_waitcnt vmcnt(2)
	v_lshlrev_b32_e32 v36, 16, v123
	v_and_b32_e32 v37, 0xffff0000, v123
	v_pk_add_f32 v[44:45], v[64:65], v[72:73]
	v_lshlrev_b32_e32 v64, 16, v122
	v_and_b32_e32 v65, 0xffff0000, v122
	v_pk_add_f32 v[42:43], v[42:43], v[50:51]
	v_and_b32_e32 v51, 0xffff0000, v121
	v_pk_add_f32 v[54:55], v[66:67], v[74:75]
	v_mul_f32_e32 v84, 0xbfb8aa3b, v38
	v_mul_f32_e32 v87, 0xbfb8aa3b, v63
	v_mul_f32_e32 v90, 0xbfb8aa3b, v64
	v_mul_f32_e32 v93, 0xbfb8aa3b, v51
	v_pk_mul_f32 v[80:81], v[54:55], v[54:55]
	v_pk_mul_f32 v[78:79], v[42:43], v[42:43]
	v_exp_f32_e32 v84, v84
	v_exp_f32_e32 v87, v87
	v_exp_f32_e32 v90, v90
	v_exp_f32_e32 v93, v93
	v_add_f32_e32 v80, v80, v81
	v_add_f32_e32 v78, v78, v80
	v_pk_mul_f32 v[76:77], v[44:45], v[44:45]
	v_add_f32_e32 v78, v79, v78
	v_add_f32_e32 v76, v76, v78
	v_pk_mul_f32 v[74:75], v[28:29], v[28:29]
	v_add_f32_e32 v80, 1.0, v84
	v_add_f32_e32 v84, 1.0, v87
	v_add_f32_e32 v87, 1.0, v90
	v_add_f32_e32 v90, 1.0, v93
	v_add_f32_e32 v93, v77, v76
	v_add_f32_e32 v74, v74, v93
	v_pk_mul_f32 v[72:73], v[46:47], v[46:47]
	v_add_f32_e32 v74, v75, v74
	v_add_f32_e32 v72, v72, v74
	v_pk_mul_f32 v[70:71], v[30:31], v[30:31]
	v_add_f32_e32 v72, v73, v72
	v_add_f32_e32 v70, v70, v72
	v_pk_mul_f32 v[68:69], v[58:59], v[58:59]
	v_add_f32_e32 v70, v71, v70
	v_add_f32_e32 v68, v68, v70
	v_lshlrev_b32_e32 v50, 16, v121
	v_lshlrev_b32_e32 v66, 16, v120
	v_and_b32_e32 v67, 0xffff0000, v120
	s_mov_b64 s[100:101], exec
	s_andn2_b64 exec, exec, s[14:15]
	v_lshl_add_u64 v[124:125], v[24:25], 0, v[20:21]
	global_load_dwordx4 v[100:103], v[124:125], off offset:16
	global_load_dwordx4 v[104:107], v[124:125], off
	v_lshl_add_u64 v[126:127], v[124:125], 0, s[16:17]
	global_load_dwordx4 v[108:111], v[126:127], off offset:16
	global_load_dwordx4 v[112:115], v[126:127], off
	v_lshl_add_u64 v[126:127], v[22:23], 0, v[20:21]
	v_lshl_add_u64 v[126:127], v[126:127], 0, s[18:19]
	global_load_dwordx4 v[116:119], v[126:127], off offset:16
	global_load_dwordx4 v[120:123], v[126:127], off
	s_mov_b64 exec, s[100:101]
	v_pk_mul_f32 v[52:53], v[40:41], v[40:41]
	v_add_f32_e32 v68, v69, v68
	v_add_f32_e32 v52, v52, v68
	v_add_f32_e32 v52, v53, v52
	ds_bpermute_b32 v53, v32, v52
	v_mul_f32_e32 v82, 0xbfb8aa3b, v60
	v_mul_f32_e32 v83, 0xbfb8aa3b, v61
	v_mul_f32_e32 v85, 0xbfb8aa3b, v39
	v_mul_f32_e32 v86, 0xbfb8aa3b, v62
	s_waitcnt lgkmcnt(0)
	v_add_f32_e32 v52, v52, v53
	ds_bpermute_b32 v53, v33, v52
	v_mul_f32_e32 v88, 0xbfb8aa3b, v36
	v_mul_f32_e32 v89, 0xbfb8aa3b, v37
	v_mul_f32_e32 v91, 0xbfb8aa3b, v65
	v_mul_f32_e32 v92, 0xbfb8aa3b, v50
	s_waitcnt lgkmcnt(0)
	v_add_f32_e32 v52, v52, v53
	ds_bpermute_b32 v53, v34, v52
	v_mul_f32_e32 v94, 0xbfb8aa3b, v66
	v_mul_f32_e32 v95, 0xbfb8aa3b, v67
	v_mul_f32_e32 v96, 0xbfb8aa3b, v48
	v_mul_f32_e32 v97, 0xbfb8aa3b, v49
	s_waitcnt lgkmcnt(0)
	v_add_f32_e32 v52, v52, v53
	ds_bpermute_b32 v53, v35, v52
	v_exp_f32_e32 v82, v82
	v_exp_f32_e32 v83, v83
	v_exp_f32_e32 v85, v85
	v_exp_f32_e32 v86, v86
	s_waitcnt lgkmcnt(0)
	v_add_f32_e32 v52, v52, v53
	v_fmamk_f32 v52, v52, 0x3b800000, v19
	v_exp_f32_e32 v88, v88
	v_exp_f32_e32 v89, v89
	v_exp_f32_e32 v91, v91
	v_exp_f32_e32 v92, v92
	v_exp_f32_e32 v94, v94
	v_exp_f32_e32 v95, v95
	v_mul_f32_e32 v53, 0x4b800000, v52
	v_cmp_gt_f32_e32 vcc, s9, v52
	v_exp_f32_e32 v81, v96
	v_exp_f32_e32 v96, v97
	v_cndmask_b32_e32 v52, v52, v53, vcc
	v_rsq_f32_e32 v52, v52
	v_add_f32_e32 v78, 1.0, v82
	v_add_f32_e32 v79, 1.0, v83
	v_add_f32_e32 v82, 1.0, v85
	v_add_f32_e32 v83, 1.0, v86
	v_add_f32_e32 v85, 1.0, v88
	v_add_f32_e32 v86, 1.0, v89
	v_add_f32_e32 v88, 1.0, v91
	v_add_f32_e32 v89, 1.0, v92
	v_add_f32_e32 v91, 1.0, v94
	v_add_f32_e32 v92, 1.0, v95
	v_add_f32_e32 v94, 1.0, v81
	v_add_f32_e32 v95, 1.0, v96
	v_rcp_f32_e32 v76, v78
	v_rcp_f32_e32 v77, v79
	v_rcp_f32_e32 v78, v80
	v_rcp_f32_e32 v79, v82
	v_rcp_f32_e32 v80, v83
	v_rcp_f32_e32 v81, v84
	v_rcp_f32_e32 v82, v85
	v_rcp_f32_e32 v83, v86
	v_rcp_f32_e32 v84, v87
	v_rcp_f32_e32 v85, v88
	v_rcp_f32_e32 v86, v89
	v_rcp_f32_e32 v87, v90
	v_rcp_f32_e32 v88, v91
	v_rcp_f32_e32 v89, v92
	v_rcp_f32_e32 v90, v94
	v_rcp_f32_e32 v91, v95
	v_mul_f32_e32 v53, 0x45800000, v52
	v_cndmask_b32_e32 v52, v52, v53, vcc
	v_pk_mul_f32 v[54:55], v[54:55], v[52:53] op_sel_hi:[1,0]
	v_pk_mul_f32 v[42:43], v[42:43], v[52:53] op_sel_hi:[1,0]
	v_pk_mul_f32 v[44:45], v[44:45], v[52:53] op_sel_hi:[1,0]
	v_pk_mul_f32 v[28:29], v[28:29], v[52:53] op_sel_hi:[1,0]
	v_pk_mul_f32 v[36:37], v[82:83], v[36:37]
	v_pk_mul_f32 v[64:65], v[84:85], v[64:65]
	v_pk_mul_f32 v[50:51], v[86:87], v[50:51]
	v_pk_mul_f32 v[66:67], v[88:89], v[66:67]
	v_pk_mul_f32 v[46:47], v[46:47], v[52:53] op_sel_hi:[1,0]
	v_pk_mul_f32 v[30:31], v[30:31], v[52:53] op_sel_hi:[1,0]
	v_pk_mul_f32 v[58:59], v[58:59], v[52:53] op_sel_hi:[1,0]
	v_pk_mul_f32 v[40:41], v[40:41], v[52:53] op_sel_hi:[1,0]
	v_pk_mul_f32 v[52:53], v[2:3], v[54:55]
	v_pk_mul_f32 v[42:43], v[4:5], v[42:43]
	v_pk_mul_f32 v[44:45], v[6:7], v[44:45]
	v_pk_mul_f32 v[28:29], v[8:9], v[28:29]
	v_pk_mul_f32 v[60:61], v[76:77], v[60:61]
	v_pk_mul_f32 v[38:39], v[78:79], v[38:39]
	v_pk_mul_f32 v[62:63], v[80:81], v[62:63]
	v_pk_mul_f32 v[48:49], v[90:91], v[48:49]
	v_pk_mul_f32 v[46:47], v[10:11], v[46:47]
	v_pk_mul_f32 v[30:31], v[12:13], v[30:31]
	v_pk_mul_f32 v[54:55], v[14:15], v[58:59]
	v_pk_mul_f32 v[40:41], v[16:17], v[40:41]
	v_pk_mul_f32 v[52:53], v[66:67], v[52:53]
	v_pk_mul_f32 v[42:43], v[50:51], v[42:43]
	v_pk_mul_f32 v[44:45], v[64:65], v[44:45]
	v_pk_mul_f32 v[36:37], v[36:37], v[28:29]
	v_pk_mul_f32 v[46:47], v[62:63], v[46:47]
	v_pk_mul_f32 v[38:39], v[38:39], v[30:31]
	v_pk_mul_f32 v[50:51], v[60:61], v[54:55]
	v_pk_mul_f32 v[40:41], v[48:49], v[40:41]
	v_cvt_pk_bf16_f32 v28, v52, v53
	v_cvt_pk_bf16_f32 v29, v42, v43
	v_cvt_pk_bf16_f32 v30, v44, v45
	v_cvt_pk_bf16_f32 v31, v36, v37
	v_cvt_pk_bf16_f32 v36, v46, v47
	v_cvt_pk_bf16_f32 v37, v38, v39
	v_cvt_pk_bf16_f32 v38, v50, v51
	v_cvt_pk_bf16_f32 v39, v40, v41
	global_store_dwordx4 v[56:57], v[28:31], off
	global_store_dwordx4 v[56:57], v[36:39], off offset:16
	s_andn2_b64 exec, exec, s[14:15]
	s_cbranch_execnz .LBB0_1055
